# scan recurrence loop: next chunk's LDS addresses and the loop test computed in front of the chunk barrier (back edge rotated out of the head)
# baseline (speedup 1.0000x reference)
.LBB0_1110:
	s_ashr_i32 s16, s44, 6
	s_ashr_i32 s17, s16, 31
	s_and_b32 s12, s44, 3
	s_bfe_u32 s13, s44, 0x40002
	s_lshl_b64 s[94:95], s[16:17], 12
	s_barrier
	s_and_saveexec_b64 s[8:9], s[0:1]
	s_xor_b64 s[8:9], exec, s[8:9]
	s_cbranch_execz .LBB0_1114
	s_waitcnt lgkmcnt(0)
	s_barrier
	s_mov_b32 s10, 0
	s_waitcnt vmcnt(22)
	v_mov_b32_e32 v0, 0
	v_mov_b32_e32 v1, 0
	v_mov_b32_e32 v2, 0
	v_mov_b32_e32 v3, 0
	s_waitcnt vmcnt(0)
	s_and_b32 s11, s10, 1
	s_mul_i32 s18, s11, 0x4e00
	v_lshl_add_u32 v131, s11, 14, v21
	v_lshl_add_u32 v130, v20, 2, s18
	v_mov_b32_e32 v129, s18
	v_lshl_add_u32 v128, v16, 2, s18
	s_add_i32 s10, s10, 1
.LBB0_1112:
	ds_read_b128 v[44:47], v130 offset:0
	ds_read_b128 v[48:51], v130 offset:256
	ds_read_b128 v[52:55], v130 offset:512
	ds_read_b128 v[56:59], v130 offset:768
	ds_read_b128 v[60:63], v130 offset:1024
	ds_read_b128 v[64:67], v130 offset:1280
	ds_read_b128 v[68:71], v130 offset:1536
	ds_read_b128 v[72:75], v130 offset:1792
	ds_read_b128 v[76:79], v130 offset:2048
	ds_read_b128 v[80:83], v129 offset:2432
	ds_read_b128 v[84:87], v129 offset:2448
	ds_read_b32 v89, v128 offset:2304
	ds_read_b32 v91, v128 offset:2368
	s_waitcnt lgkmcnt(11)
	v_pk_mul_f32 v[4:5], v[0:1], v[44:45]
	v_pk_mul_f32 v[6:7], v[0:1], v[48:49]
	v_pk_fma_f32 v[4:5], v[2:3], v[46:47], v[4:5]
	v_pk_fma_f32 v[6:7], v[2:3], v[50:51], v[6:7]
	v_add_f32_e32 v22, v4, v5
	v_add_f32_e32 v42, v6, v7
	ds_read_b128 v[196:199], v130 offset:2496
	ds_read_b128 v[200:203], v130 offset:2752
	ds_read_b128 v[204:207], v130 offset:3008
	ds_read_b128 v[208:211], v130 offset:3264
	ds_read_b128 v[212:215], v130 offset:3520
	ds_read_b128 v[216:219], v130 offset:3776
	ds_read_b128 v[220:223], v130 offset:4032
	ds_read_b128 v[224:227], v130 offset:4288
	ds_read_b128 v[228:231], v130 offset:4544
	ds_read_b128 v[232:235], v129 offset:4928
	ds_read_b128 v[236:239], v129 offset:4944
	ds_read_b32 v241, v128 offset:4800
	ds_read_b32 v243, v128 offset:4864
	s_waitcnt lgkmcnt(13)
	v_pk_mul_f32 v[8:9], v[0:1], v[52:53]
	v_add_f32_dpp v22, v22, v22 quad_perm:[1,0,3,2] row_mask:0xf bank_mask:0xf bound_ctrl:1
	v_add_f32_dpp v42, v42, v42 quad_perm:[1,0,3,2] row_mask:0xf bank_mask:0xf bound_ctrl:1
	v_pk_mul_f32 v[10:11], v[2:3], v[54:55]
	v_add_f32_dpp v22, v22, v22 quad_perm:[2,3,0,1] row_mask:0xf bank_mask:0xf bound_ctrl:1
	v_add_f32_dpp v42, v42, v42 quad_perm:[2,3,0,1] row_mask:0xf bank_mask:0xf bound_ctrl:1
	v_pk_mul_f32 v[12:13], v[0:1], v[72:73]
	v_add_f32_dpp v22, v22, v22 row_ror:4 row_mask:0xf bank_mask:0xf bound_ctrl:1
	v_add_f32_dpp v42, v42, v42 row_ror:4 row_mask:0xf bank_mask:0xf bound_ctrl:1
	v_pk_mul_f32 v[14:15], v[0:1], v[76:77]
	v_add_f32_dpp v88, v22, v22 row_ror:8 row_mask:0xf bank_mask:0xf bound_ctrl:1
	v_add_f32_dpp v42, v42, v42 row_ror:8 row_mask:0xf bank_mask:0xf bound_ctrl:1
	v_pk_fma_f32 v[8:9], v[88:89], v[60:61], v[8:9] op_sel:[1,0,0] op_sel_hi:[1,1,1]
	v_pk_fma_f32 v[10:11], v[88:89], v[62:63], v[10:11] op_sel:[1,0,0] op_sel_hi:[1,1,1]
	v_fma_f32 v4, v88, v80, v42
	v_pk_fma_f32 v[8:9], v[90:91], v[68:69], v[8:9] op_sel:[1,0,0] op_sel_hi:[1,1,1]
	v_fma_f32 v90, v89, v81, v4
	v_pk_fma_f32 v[10:11], v[90:91], v[70:71], v[10:11] op_sel:[1,0,0] op_sel_hi:[1,1,1]
	v_pk_fma_f32 v[12:13], v[2:3], v[74:75], v[12:13]
	v_pk_fma_f32 v[14:15], v[2:3], v[78:79], v[14:15]
	v_pk_fma_f32 v[0:1], v[88:89], v[56:57], v[8:9] op_sel:[0,0,0] op_sel_hi:[0,1,1]
	v_pk_fma_f32 v[2:3], v[88:89], v[58:59], v[10:11] op_sel:[0,0,0] op_sel_hi:[0,1,1]
	v_pk_fma_f32 v[0:1], v[90:91], v[64:65], v[0:1] op_sel:[0,0,0] op_sel_hi:[0,1,1]
	v_pk_fma_f32 v[2:3], v[90:91], v[66:67], v[2:3] op_sel:[0,0,0] op_sel_hi:[0,1,1]
	v_pk_fma_f32 v[12:13], v[88:89], v[82:83], v[12:13]
	v_pk_fma_f32 v[14:15], v[90:91], v[86:87], v[14:15]
	v_pk_fma_f32 v[14:15], v[88:89], v[84:85], v[14:15]
	v_add_f32_e32 v126, v12, v13
	v_add_f32_e32 v127, v14, v15
	ds_read_b128 v[44:47], v130 offset:4992
	ds_read_b128 v[48:51], v130 offset:5248
	ds_read_b128 v[52:55], v130 offset:5504
	ds_read_b128 v[56:59], v130 offset:5760
	ds_read_b128 v[60:63], v130 offset:6016
	ds_read_b128 v[64:67], v130 offset:6272
	ds_read_b128 v[68:71], v130 offset:6528
	ds_read_b128 v[72:75], v130 offset:6784
	ds_read_b128 v[76:79], v130 offset:7040
	ds_read_b128 v[80:83], v129 offset:7424
	ds_read_b128 v[84:87], v129 offset:7440
	ds_read_b32 v89, v128 offset:7296
	ds_read_b32 v91, v128 offset:7360
	ds_write2st64_b32 v131, v126, v127 offset0:156 offset1:160
	s_waitcnt lgkmcnt(14)
	v_pk_mul_f32 v[4:5], v[0:1], v[196:197]
	v_pk_mul_f32 v[6:7], v[0:1], v[200:201]
	v_pk_fma_f32 v[4:5], v[2:3], v[198:199], v[4:5]
	v_pk_fma_f32 v[6:7], v[2:3], v[202:203], v[6:7]
	v_add_f32_e32 v22, v4, v5
	v_add_f32_e32 v42, v6, v7
	v_pk_mul_f32 v[8:9], v[0:1], v[204:205]
	v_add_f32_dpp v22, v22, v22 quad_perm:[1,0,3,2] row_mask:0xf bank_mask:0xf bound_ctrl:1
	v_add_f32_dpp v42, v42, v42 quad_perm:[1,0,3,2] row_mask:0xf bank_mask:0xf bound_ctrl:1
	v_pk_mul_f32 v[10:11], v[2:3], v[206:207]
	v_add_f32_dpp v22, v22, v22 quad_perm:[2,3,0,1] row_mask:0xf bank_mask:0xf bound_ctrl:1
	v_add_f32_dpp v42, v42, v42 quad_perm:[2,3,0,1] row_mask:0xf bank_mask:0xf bound_ctrl:1
	v_pk_mul_f32 v[12:13], v[0:1], v[224:225]
	v_add_f32_dpp v22, v22, v22 row_ror:4 row_mask:0xf bank_mask:0xf bound_ctrl:1
	v_add_f32_dpp v42, v42, v42 row_ror:4 row_mask:0xf bank_mask:0xf bound_ctrl:1
	v_pk_mul_f32 v[14:15], v[0:1], v[228:229]
	v_add_f32_dpp v240, v22, v22 row_ror:8 row_mask:0xf bank_mask:0xf bound_ctrl:1
	v_add_f32_dpp v42, v42, v42 row_ror:8 row_mask:0xf bank_mask:0xf bound_ctrl:1
	v_pk_fma_f32 v[8:9], v[240:241], v[212:213], v[8:9] op_sel:[1,0,0] op_sel_hi:[1,1,1]
	v_pk_fma_f32 v[10:11], v[240:241], v[214:215], v[10:11] op_sel:[1,0,0] op_sel_hi:[1,1,1]
	v_fma_f32 v4, v240, v232, v42
	v_pk_fma_f32 v[8:9], v[242:243], v[220:221], v[8:9] op_sel:[1,0,0] op_sel_hi:[1,1,1]
	v_fma_f32 v242, v241, v233, v4
	v_pk_fma_f32 v[10:11], v[242:243], v[222:223], v[10:11] op_sel:[1,0,0] op_sel_hi:[1,1,1]
	v_pk_fma_f32 v[12:13], v[2:3], v[226:227], v[12:13]
	v_pk_fma_f32 v[14:15], v[2:3], v[230:231], v[14:15]
	v_pk_fma_f32 v[0:1], v[240:241], v[208:209], v[8:9] op_sel:[0,0,0] op_sel_hi:[0,1,1]
	v_pk_fma_f32 v[2:3], v[240:241], v[210:211], v[10:11] op_sel:[0,0,0] op_sel_hi:[0,1,1]
	v_pk_fma_f32 v[0:1], v[242:243], v[216:217], v[0:1] op_sel:[0,0,0] op_sel_hi:[0,1,1]
	v_pk_fma_f32 v[2:3], v[242:243], v[218:219], v[2:3] op_sel:[0,0,0] op_sel_hi:[0,1,1]
	v_pk_fma_f32 v[12:13], v[240:241], v[234:235], v[12:13]
	v_pk_fma_f32 v[14:15], v[242:243], v[238:239], v[14:15]
	v_pk_fma_f32 v[14:15], v[240:241], v[236:237], v[14:15]
	v_add_f32_e32 v126, v12, v13
	v_add_f32_e32 v127, v14, v15
	ds_read_b128 v[196:199], v130 offset:7488
	ds_read_b128 v[200:203], v130 offset:7744
	ds_read_b128 v[204:207], v130 offset:8000
	ds_read_b128 v[208:211], v130 offset:8256
	ds_read_b128 v[212:215], v130 offset:8512
	ds_read_b128 v[216:219], v130 offset:8768
	ds_read_b128 v[220:223], v130 offset:9024
	ds_read_b128 v[224:227], v130 offset:9280
	ds_read_b128 v[228:231], v130 offset:9536
	ds_read_b128 v[232:235], v129 offset:9920
	ds_read_b128 v[236:239], v129 offset:9936
	ds_read_b32 v241, v128 offset:9792
	ds_read_b32 v243, v128 offset:9856
	ds_write2st64_b32 v131, v126, v127 offset0:164 offset1:168
	s_waitcnt lgkmcnt(14)
	v_pk_mul_f32 v[4:5], v[0:1], v[44:45]
	v_pk_mul_f32 v[6:7], v[0:1], v[48:49]
	v_pk_fma_f32 v[4:5], v[2:3], v[46:47], v[4:5]
	v_pk_fma_f32 v[6:7], v[2:3], v[50:51], v[6:7]
	v_add_f32_e32 v22, v4, v5
	v_add_f32_e32 v42, v6, v7
	v_pk_mul_f32 v[8:9], v[0:1], v[52:53]
	v_add_f32_dpp v22, v22, v22 quad_perm:[1,0,3,2] row_mask:0xf bank_mask:0xf bound_ctrl:1
	v_add_f32_dpp v42, v42, v42 quad_perm:[1,0,3,2] row_mask:0xf bank_mask:0xf bound_ctrl:1
	v_pk_mul_f32 v[10:11], v[2:3], v[54:55]
	v_add_f32_dpp v22, v22, v22 quad_perm:[2,3,0,1] row_mask:0xf bank_mask:0xf bound_ctrl:1
	v_add_f32_dpp v42, v42, v42 quad_perm:[2,3,0,1] row_mask:0xf bank_mask:0xf bound_ctrl:1
	v_pk_mul_f32 v[12:13], v[0:1], v[72:73]
	v_add_f32_dpp v22, v22, v22 row_ror:4 row_mask:0xf bank_mask:0xf bound_ctrl:1
	v_add_f32_dpp v42, v42, v42 row_ror:4 row_mask:0xf bank_mask:0xf bound_ctrl:1
	v_pk_mul_f32 v[14:15], v[0:1], v[76:77]
	v_add_f32_dpp v88, v22, v22 row_ror:8 row_mask:0xf bank_mask:0xf bound_ctrl:1
	v_add_f32_dpp v42, v42, v42 row_ror:8 row_mask:0xf bank_mask:0xf bound_ctrl:1
	v_pk_fma_f32 v[8:9], v[88:89], v[60:61], v[8:9] op_sel:[1,0,0] op_sel_hi:[1,1,1]
	v_pk_fma_f32 v[10:11], v[88:89], v[62:63], v[10:11] op_sel:[1,0,0] op_sel_hi:[1,1,1]
	v_fma_f32 v4, v88, v80, v42
	v_pk_fma_f32 v[8:9], v[90:91], v[68:69], v[8:9] op_sel:[1,0,0] op_sel_hi:[1,1,1]
	v_fma_f32 v90, v89, v81, v4
	v_pk_fma_f32 v[10:11], v[90:91], v[70:71], v[10:11] op_sel:[1,0,0] op_sel_hi:[1,1,1]
	v_pk_fma_f32 v[12:13], v[2:3], v[74:75], v[12:13]
	v_pk_fma_f32 v[14:15], v[2:3], v[78:79], v[14:15]
	v_pk_fma_f32 v[0:1], v[88:89], v[56:57], v[8:9] op_sel:[0,0,0] op_sel_hi:[0,1,1]
	v_pk_fma_f32 v[2:3], v[88:89], v[58:59], v[10:11] op_sel:[0,0,0] op_sel_hi:[0,1,1]
	v_pk_fma_f32 v[0:1], v[90:91], v[64:65], v[0:1] op_sel:[0,0,0] op_sel_hi:[0,1,1]
	v_pk_fma_f32 v[2:3], v[90:91], v[66:67], v[2:3] op_sel:[0,0,0] op_sel_hi:[0,1,1]
	v_pk_fma_f32 v[12:13], v[88:89], v[82:83], v[12:13]
	v_pk_fma_f32 v[14:15], v[90:91], v[86:87], v[14:15]
	v_pk_fma_f32 v[14:15], v[88:89], v[84:85], v[14:15]
	v_add_f32_e32 v126, v12, v13
	v_add_f32_e32 v127, v14, v15
	ds_read_b128 v[44:47], v130 offset:9984
	ds_read_b128 v[48:51], v130 offset:10240
	ds_read_b128 v[52:55], v130 offset:10496
	ds_read_b128 v[56:59], v130 offset:10752
	ds_read_b128 v[60:63], v130 offset:11008
	ds_read_b128 v[64:67], v130 offset:11264
	ds_read_b128 v[68:71], v130 offset:11520
	ds_read_b128 v[72:75], v130 offset:11776
	ds_read_b128 v[76:79], v130 offset:12032
	ds_read_b128 v[80:83], v129 offset:12416
	ds_read_b128 v[84:87], v129 offset:12432
	ds_read_b32 v89, v128 offset:12288
	ds_read_b32 v91, v128 offset:12352
	ds_write2st64_b32 v131, v126, v127 offset0:172 offset1:176
	s_waitcnt lgkmcnt(14)
	v_pk_mul_f32 v[4:5], v[0:1], v[196:197]
	v_pk_mul_f32 v[6:7], v[0:1], v[200:201]
	v_pk_fma_f32 v[4:5], v[2:3], v[198:199], v[4:5]
	v_pk_fma_f32 v[6:7], v[2:3], v[202:203], v[6:7]
	v_add_f32_e32 v22, v4, v5
	v_add_f32_e32 v42, v6, v7
	v_pk_mul_f32 v[8:9], v[0:1], v[204:205]
	v_add_f32_dpp v22, v22, v22 quad_perm:[1,0,3,2] row_mask:0xf bank_mask:0xf bound_ctrl:1
	v_add_f32_dpp v42, v42, v42 quad_perm:[1,0,3,2] row_mask:0xf bank_mask:0xf bound_ctrl:1
	v_pk_mul_f32 v[10:11], v[2:3], v[206:207]
	v_add_f32_dpp v22, v22, v22 quad_perm:[2,3,0,1] row_mask:0xf bank_mask:0xf bound_ctrl:1
	v_add_f32_dpp v42, v42, v42 quad_perm:[2,3,0,1] row_mask:0xf bank_mask:0xf bound_ctrl:1
	v_pk_mul_f32 v[12:13], v[0:1], v[224:225]
	v_add_f32_dpp v22, v22, v22 row_ror:4 row_mask:0xf bank_mask:0xf bound_ctrl:1
	v_add_f32_dpp v42, v42, v42 row_ror:4 row_mask:0xf bank_mask:0xf bound_ctrl:1
	v_pk_mul_f32 v[14:15], v[0:1], v[228:229]
	v_add_f32_dpp v240, v22, v22 row_ror:8 row_mask:0xf bank_mask:0xf bound_ctrl:1
	v_add_f32_dpp v42, v42, v42 row_ror:8 row_mask:0xf bank_mask:0xf bound_ctrl:1
	v_pk_fma_f32 v[8:9], v[240:241], v[212:213], v[8:9] op_sel:[1,0,0] op_sel_hi:[1,1,1]
	v_pk_fma_f32 v[10:11], v[240:241], v[214:215], v[10:11] op_sel:[1,0,0] op_sel_hi:[1,1,1]
	v_fma_f32 v4, v240, v232, v42
	v_pk_fma_f32 v[8:9], v[242:243], v[220:221], v[8:9] op_sel:[1,0,0] op_sel_hi:[1,1,1]
	v_fma_f32 v242, v241, v233, v4
	v_pk_fma_f32 v[10:11], v[242:243], v[222:223], v[10:11] op_sel:[1,0,0] op_sel_hi:[1,1,1]
	v_pk_fma_f32 v[12:13], v[2:3], v[226:227], v[12:13]
	v_pk_fma_f32 v[14:15], v[2:3], v[230:231], v[14:15]
	v_pk_fma_f32 v[0:1], v[240:241], v[208:209], v[8:9] op_sel:[0,0,0] op_sel_hi:[0,1,1]
	v_pk_fma_f32 v[2:3], v[240:241], v[210:211], v[10:11] op_sel:[0,0,0] op_sel_hi:[0,1,1]
	v_pk_fma_f32 v[0:1], v[242:243], v[216:217], v[0:1] op_sel:[0,0,0] op_sel_hi:[0,1,1]
	v_pk_fma_f32 v[2:3], v[242:243], v[218:219], v[2:3] op_sel:[0,0,0] op_sel_hi:[0,1,1]
	v_pk_fma_f32 v[12:13], v[240:241], v[234:235], v[12:13]
	v_pk_fma_f32 v[14:15], v[242:243], v[238:239], v[14:15]
	v_pk_fma_f32 v[14:15], v[240:241], v[236:237], v[14:15]
	v_add_f32_e32 v126, v12, v13
	v_add_f32_e32 v127, v14, v15
	ds_read_b128 v[196:199], v130 offset:12480
	ds_read_b128 v[200:203], v130 offset:12736
	ds_read_b128 v[204:207], v130 offset:12992
	ds_read_b128 v[208:211], v130 offset:13248
	ds_read_b128 v[212:215], v130 offset:13504
	ds_read_b128 v[216:219], v130 offset:13760
	ds_read_b128 v[220:223], v130 offset:14016
	ds_read_b128 v[224:227], v130 offset:14272
	ds_read_b128 v[228:231], v130 offset:14528
	ds_read_b128 v[232:235], v129 offset:14912
	ds_read_b128 v[236:239], v129 offset:14928
	ds_read_b32 v241, v128 offset:14784
	ds_read_b32 v243, v128 offset:14848
	ds_write2st64_b32 v131, v126, v127 offset0:180 offset1:184
	s_waitcnt lgkmcnt(14)
	v_pk_mul_f32 v[4:5], v[0:1], v[44:45]
	v_pk_mul_f32 v[6:7], v[0:1], v[48:49]
	v_pk_fma_f32 v[4:5], v[2:3], v[46:47], v[4:5]
	v_pk_fma_f32 v[6:7], v[2:3], v[50:51], v[6:7]
	v_add_f32_e32 v22, v4, v5
	v_add_f32_e32 v42, v6, v7
	v_pk_mul_f32 v[8:9], v[0:1], v[52:53]
	v_add_f32_dpp v22, v22, v22 quad_perm:[1,0,3,2] row_mask:0xf bank_mask:0xf bound_ctrl:1
	v_add_f32_dpp v42, v42, v42 quad_perm:[1,0,3,2] row_mask:0xf bank_mask:0xf bound_ctrl:1
	v_pk_mul_f32 v[10:11], v[2:3], v[54:55]
	v_add_f32_dpp v22, v22, v22 quad_perm:[2,3,0,1] row_mask:0xf bank_mask:0xf bound_ctrl:1
	v_add_f32_dpp v42, v42, v42 quad_perm:[2,3,0,1] row_mask:0xf bank_mask:0xf bound_ctrl:1
	v_pk_mul_f32 v[12:13], v[0:1], v[72:73]
	v_add_f32_dpp v22, v22, v22 row_ror:4 row_mask:0xf bank_mask:0xf bound_ctrl:1
	v_add_f32_dpp v42, v42, v42 row_ror:4 row_mask:0xf bank_mask:0xf bound_ctrl:1
	v_pk_mul_f32 v[14:15], v[0:1], v[76:77]
	v_add_f32_dpp v88, v22, v22 row_ror:8 row_mask:0xf bank_mask:0xf bound_ctrl:1
	v_add_f32_dpp v42, v42, v42 row_ror:8 row_mask:0xf bank_mask:0xf bound_ctrl:1
	v_pk_fma_f32 v[8:9], v[88:89], v[60:61], v[8:9] op_sel:[1,0,0] op_sel_hi:[1,1,1]
	v_pk_fma_f32 v[10:11], v[88:89], v[62:63], v[10:11] op_sel:[1,0,0] op_sel_hi:[1,1,1]
	v_fma_f32 v4, v88, v80, v42
	v_pk_fma_f32 v[8:9], v[90:91], v[68:69], v[8:9] op_sel:[1,0,0] op_sel_hi:[1,1,1]
	v_fma_f32 v90, v89, v81, v4
	v_pk_fma_f32 v[10:11], v[90:91], v[70:71], v[10:11] op_sel:[1,0,0] op_sel_hi:[1,1,1]
	v_pk_fma_f32 v[12:13], v[2:3], v[74:75], v[12:13]
	v_pk_fma_f32 v[14:15], v[2:3], v[78:79], v[14:15]
	v_pk_fma_f32 v[0:1], v[88:89], v[56:57], v[8:9] op_sel:[0,0,0] op_sel_hi:[0,1,1]
	v_pk_fma_f32 v[2:3], v[88:89], v[58:59], v[10:11] op_sel:[0,0,0] op_sel_hi:[0,1,1]
	v_pk_fma_f32 v[0:1], v[90:91], v[64:65], v[0:1] op_sel:[0,0,0] op_sel_hi:[0,1,1]
	v_pk_fma_f32 v[2:3], v[90:91], v[66:67], v[2:3] op_sel:[0,0,0] op_sel_hi:[0,1,1]
	v_pk_fma_f32 v[12:13], v[88:89], v[82:83], v[12:13]
	v_pk_fma_f32 v[14:15], v[90:91], v[86:87], v[14:15]
	v_pk_fma_f32 v[14:15], v[88:89], v[84:85], v[14:15]
	v_add_f32_e32 v126, v12, v13
	v_add_f32_e32 v127, v14, v15
	ds_read_b128 v[44:47], v130 offset:14976
	ds_read_b128 v[48:51], v130 offset:15232
	ds_read_b128 v[52:55], v130 offset:15488
	ds_read_b128 v[56:59], v130 offset:15744
	ds_read_b128 v[60:63], v130 offset:16000
	ds_read_b128 v[64:67], v130 offset:16256
	ds_read_b128 v[68:71], v130 offset:16512
	ds_read_b128 v[72:75], v130 offset:16768
	ds_read_b128 v[76:79], v130 offset:17024
	ds_read_b128 v[80:83], v129 offset:17408
	ds_read_b128 v[84:87], v129 offset:17424
	ds_read_b32 v89, v128 offset:17280
	ds_read_b32 v91, v128 offset:17344
	ds_write2st64_b32 v131, v126, v127 offset0:188 offset1:192
	s_waitcnt lgkmcnt(14)
	v_pk_mul_f32 v[4:5], v[0:1], v[196:197]
	v_pk_mul_f32 v[6:7], v[0:1], v[200:201]
	v_pk_fma_f32 v[4:5], v[2:3], v[198:199], v[4:5]
	v_pk_fma_f32 v[6:7], v[2:3], v[202:203], v[6:7]
	v_add_f32_e32 v22, v4, v5
	v_add_f32_e32 v42, v6, v7
	v_pk_mul_f32 v[8:9], v[0:1], v[204:205]
	v_add_f32_dpp v22, v22, v22 quad_perm:[1,0,3,2] row_mask:0xf bank_mask:0xf bound_ctrl:1
	v_add_f32_dpp v42, v42, v42 quad_perm:[1,0,3,2] row_mask:0xf bank_mask:0xf bound_ctrl:1
	v_pk_mul_f32 v[10:11], v[2:3], v[206:207]
	v_add_f32_dpp v22, v22, v22 quad_perm:[2,3,0,1] row_mask:0xf bank_mask:0xf bound_ctrl:1
	v_add_f32_dpp v42, v42, v42 quad_perm:[2,3,0,1] row_mask:0xf bank_mask:0xf bound_ctrl:1
	v_pk_mul_f32 v[12:13], v[0:1], v[224:225]
	v_add_f32_dpp v22, v22, v22 row_ror:4 row_mask:0xf bank_mask:0xf bound_ctrl:1
	v_add_f32_dpp v42, v42, v42 row_ror:4 row_mask:0xf bank_mask:0xf bound_ctrl:1
	v_pk_mul_f32 v[14:15], v[0:1], v[228:229]
	v_add_f32_dpp v240, v22, v22 row_ror:8 row_mask:0xf bank_mask:0xf bound_ctrl:1
	v_add_f32_dpp v42, v42, v42 row_ror:8 row_mask:0xf bank_mask:0xf bound_ctrl:1
	v_pk_fma_f32 v[8:9], v[240:241], v[212:213], v[8:9] op_sel:[1,0,0] op_sel_hi:[1,1,1]
	v_pk_fma_f32 v[10:11], v[240:241], v[214:215], v[10:11] op_sel:[1,0,0] op_sel_hi:[1,1,1]
	v_fma_f32 v4, v240, v232, v42
	v_pk_fma_f32 v[8:9], v[242:243], v[220:221], v[8:9] op_sel:[1,0,0] op_sel_hi:[1,1,1]
	v_fma_f32 v242, v241, v233, v4
	v_pk_fma_f32 v[10:11], v[242:243], v[222:223], v[10:11] op_sel:[1,0,0] op_sel_hi:[1,1,1]
	v_pk_fma_f32 v[12:13], v[2:3], v[226:227], v[12:13]
	v_pk_fma_f32 v[14:15], v[2:3], v[230:231], v[14:15]
	v_pk_fma_f32 v[0:1], v[240:241], v[208:209], v[8:9] op_sel:[0,0,0] op_sel_hi:[0,1,1]
	v_pk_fma_f32 v[2:3], v[240:241], v[210:211], v[10:11] op_sel:[0,0,0] op_sel_hi:[0,1,1]
	v_pk_fma_f32 v[0:1], v[242:243], v[216:217], v[0:1] op_sel:[0,0,0] op_sel_hi:[0,1,1]
	v_pk_fma_f32 v[2:3], v[242:243], v[218:219], v[2:3] op_sel:[0,0,0] op_sel_hi:[0,1,1]
	v_pk_fma_f32 v[12:13], v[240:241], v[234:235], v[12:13]
	v_pk_fma_f32 v[14:15], v[242:243], v[238:239], v[14:15]
	v_pk_fma_f32 v[14:15], v[240:241], v[236:237], v[14:15]
	v_add_f32_e32 v126, v12, v13
	v_add_f32_e32 v127, v14, v15
	ds_read_b128 v[196:199], v130 offset:17472
	ds_read_b128 v[200:203], v130 offset:17728
	ds_read_b128 v[204:207], v130 offset:17984
	ds_read_b128 v[208:211], v130 offset:18240
	ds_read_b128 v[212:215], v130 offset:18496
	ds_read_b128 v[216:219], v130 offset:18752
	ds_read_b128 v[220:223], v130 offset:19008
	ds_read_b128 v[224:227], v130 offset:19264
	ds_read_b128 v[228:231], v130 offset:19520
	ds_read_b128 v[232:235], v129 offset:19904
	ds_read_b128 v[236:239], v129 offset:19920
	ds_read_b32 v241, v128 offset:19776
	ds_read_b32 v243, v128 offset:19840
	ds_write2st64_b32 v131, v126, v127 offset0:196 offset1:200
	s_waitcnt lgkmcnt(14)
	v_pk_mul_f32 v[4:5], v[0:1], v[44:45]
	v_pk_mul_f32 v[6:7], v[0:1], v[48:49]
	v_pk_fma_f32 v[4:5], v[2:3], v[46:47], v[4:5]
	v_pk_fma_f32 v[6:7], v[2:3], v[50:51], v[6:7]
	v_add_f32_e32 v22, v4, v5
	v_add_f32_e32 v42, v6, v7
	v_pk_mul_f32 v[8:9], v[0:1], v[52:53]
	v_add_f32_dpp v22, v22, v22 quad_perm:[1,0,3,2] row_mask:0xf bank_mask:0xf bound_ctrl:1
	v_add_f32_dpp v42, v42, v42 quad_perm:[1,0,3,2] row_mask:0xf bank_mask:0xf bound_ctrl:1
	v_pk_mul_f32 v[10:11], v[2:3], v[54:55]
	v_add_f32_dpp v22, v22, v22 quad_perm:[2,3,0,1] row_mask:0xf bank_mask:0xf bound_ctrl:1
	v_add_f32_dpp v42, v42, v42 quad_perm:[2,3,0,1] row_mask:0xf bank_mask:0xf bound_ctrl:1
	v_pk_mul_f32 v[12:13], v[0:1], v[72:73]
	v_add_f32_dpp v22, v22, v22 row_ror:4 row_mask:0xf bank_mask:0xf bound_ctrl:1
	v_add_f32_dpp v42, v42, v42 row_ror:4 row_mask:0xf bank_mask:0xf bound_ctrl:1
	v_pk_mul_f32 v[14:15], v[0:1], v[76:77]
	v_add_f32_dpp v88, v22, v22 row_ror:8 row_mask:0xf bank_mask:0xf bound_ctrl:1
	v_add_f32_dpp v42, v42, v42 row_ror:8 row_mask:0xf bank_mask:0xf bound_ctrl:1
	v_pk_fma_f32 v[8:9], v[88:89], v[60:61], v[8:9] op_sel:[1,0,0] op_sel_hi:[1,1,1]
	v_pk_fma_f32 v[10:11], v[88:89], v[62:63], v[10:11] op_sel:[1,0,0] op_sel_hi:[1,1,1]
	v_fma_f32 v4, v88, v80, v42
	v_pk_fma_f32 v[8:9], v[90:91], v[68:69], v[8:9] op_sel:[1,0,0] op_sel_hi:[1,1,1]
	v_fma_f32 v90, v89, v81, v4
	v_pk_fma_f32 v[10:11], v[90:91], v[70:71], v[10:11] op_sel:[1,0,0] op_sel_hi:[1,1,1]
	v_pk_fma_f32 v[12:13], v[2:3], v[74:75], v[12:13]
	v_pk_fma_f32 v[14:15], v[2:3], v[78:79], v[14:15]
	v_pk_fma_f32 v[0:1], v[88:89], v[56:57], v[8:9] op_sel:[0,0,0] op_sel_hi:[0,1,1]
	v_pk_fma_f32 v[2:3], v[88:89], v[58:59], v[10:11] op_sel:[0,0,0] op_sel_hi:[0,1,1]
	v_pk_fma_f32 v[0:1], v[90:91], v[64:65], v[0:1] op_sel:[0,0,0] op_sel_hi:[0,1,1]
	v_pk_fma_f32 v[2:3], v[90:91], v[66:67], v[2:3] op_sel:[0,0,0] op_sel_hi:[0,1,1]
	v_pk_fma_f32 v[12:13], v[88:89], v[82:83], v[12:13]
	v_pk_fma_f32 v[14:15], v[90:91], v[86:87], v[14:15]
	v_pk_fma_f32 v[14:15], v[88:89], v[84:85], v[14:15]
	v_add_f32_e32 v126, v12, v13
	v_add_f32_e32 v127, v14, v15
	ds_write2st64_b32 v131, v126, v127 offset0:204 offset1:208
	s_waitcnt lgkmcnt(1)
	v_pk_mul_f32 v[4:5], v[0:1], v[196:197]
	v_pk_mul_f32 v[6:7], v[0:1], v[200:201]
	v_pk_fma_f32 v[4:5], v[2:3], v[198:199], v[4:5]
	v_pk_fma_f32 v[6:7], v[2:3], v[202:203], v[6:7]
	v_add_f32_e32 v22, v4, v5
	v_add_f32_e32 v42, v6, v7
	v_pk_mul_f32 v[8:9], v[0:1], v[204:205]
	v_add_f32_dpp v22, v22, v22 quad_perm:[1,0,3,2] row_mask:0xf bank_mask:0xf bound_ctrl:1
	v_add_f32_dpp v42, v42, v42 quad_perm:[1,0,3,2] row_mask:0xf bank_mask:0xf bound_ctrl:1
	v_pk_mul_f32 v[10:11], v[2:3], v[206:207]
	v_add_f32_dpp v22, v22, v22 quad_perm:[2,3,0,1] row_mask:0xf bank_mask:0xf bound_ctrl:1
	v_add_f32_dpp v42, v42, v42 quad_perm:[2,3,0,1] row_mask:0xf bank_mask:0xf bound_ctrl:1
	v_pk_mul_f32 v[12:13], v[0:1], v[224:225]
	v_add_f32_dpp v22, v22, v22 row_ror:4 row_mask:0xf bank_mask:0xf bound_ctrl:1
	v_add_f32_dpp v42, v42, v42 row_ror:4 row_mask:0xf bank_mask:0xf bound_ctrl:1
	v_pk_mul_f32 v[14:15], v[0:1], v[228:229]
	v_add_f32_dpp v240, v22, v22 row_ror:8 row_mask:0xf bank_mask:0xf bound_ctrl:1
	v_add_f32_dpp v42, v42, v42 row_ror:8 row_mask:0xf bank_mask:0xf bound_ctrl:1
	v_pk_fma_f32 v[8:9], v[240:241], v[212:213], v[8:9] op_sel:[1,0,0] op_sel_hi:[1,1,1]
	v_pk_fma_f32 v[10:11], v[240:241], v[214:215], v[10:11] op_sel:[1,0,0] op_sel_hi:[1,1,1]
	v_fma_f32 v4, v240, v232, v42
	v_pk_fma_f32 v[8:9], v[242:243], v[220:221], v[8:9] op_sel:[1,0,0] op_sel_hi:[1,1,1]
	v_fma_f32 v242, v241, v233, v4
	v_pk_fma_f32 v[10:11], v[242:243], v[222:223], v[10:11] op_sel:[1,0,0] op_sel_hi:[1,1,1]
	v_pk_fma_f32 v[12:13], v[2:3], v[226:227], v[12:13]
	v_pk_fma_f32 v[14:15], v[2:3], v[230:231], v[14:15]
	v_pk_fma_f32 v[0:1], v[240:241], v[208:209], v[8:9] op_sel:[0,0,0] op_sel_hi:[0,1,1]
	v_pk_fma_f32 v[2:3], v[240:241], v[210:211], v[10:11] op_sel:[0,0,0] op_sel_hi:[0,1,1]
	v_pk_fma_f32 v[0:1], v[242:243], v[216:217], v[0:1] op_sel:[0,0,0] op_sel_hi:[0,1,1]
	v_pk_fma_f32 v[2:3], v[242:243], v[218:219], v[2:3] op_sel:[0,0,0] op_sel_hi:[0,1,1]
	v_pk_fma_f32 v[12:13], v[240:241], v[234:235], v[12:13]
	v_pk_fma_f32 v[14:15], v[242:243], v[238:239], v[14:15]
	v_pk_fma_f32 v[14:15], v[240:241], v[236:237], v[14:15]
	v_add_f32_e32 v126, v12, v13
	v_add_f32_e32 v127, v14, v15
	ds_write2st64_b32 v131, v126, v127 offset0:212 offset1:216
.Lscw_a:
	s_and_b32 s11, s10, 1
	s_mul_i32 s18, s11, 0x4e00
	v_lshl_add_u32 v131, s11, 14, v21
	v_lshl_add_u32 v130, v20, 2, s18
	v_mov_b32_e32 v129, s18
	v_lshl_add_u32 v128, v16, 2, s18
	s_add_i32 s10, s10, 1
	s_cmpk_eq_i32 s10, 0x101
	s_waitcnt lgkmcnt(0)
	s_barrier
.Lscw_b:
	s_cbranch_scc0 .LBB0_1112
	ds_read_b128 v[4:7], v148 offset:56320
	ds_read_b128 v[8:11], v148 offset:56336
	ds_read_b128 v[12:15], v148 offset:56352
	ds_read_b128 v[44:47], v148 offset:56368
	v_lshlrev_b32_e32 v22, 1, v18
	s_waitcnt lgkmcnt(3)
	v_mov_b32_e32 v48, v5
	v_mov_b32_e32 v49, v6
	s_waitcnt lgkmcnt(2)
	v_mov_b32_e32 v50, v9
	v_mov_b32_e32 v51, v10
	v_mov_b32_e32 v5, v7
	v_mov_b32_e32 v9, v11
	v_pk_add_f32 v[4:5], v[48:49], v[4:5]
	v_pk_add_f32 v[6:7], v[50:51], v[8:9]
	s_waitcnt lgkmcnt(1)
	v_mov_b32_e32 v8, v13
	v_mov_b32_e32 v10, v15
	v_pk_add_f32 v[4:5], v[4:5], v[4:5] op_sel:[0,1] op_sel_hi:[1,0]
	v_pk_add_f32 v[6:7], v[6:7], v[6:7] op_sel:[0,1] op_sel_hi:[1,0]
	v_pk_add_f32 v[8:9], v[12:13], v[8:9]
	v_pk_add_f32 v[10:11], v[14:15], v[10:11]
	s_waitcnt lgkmcnt(0)
	v_mov_b32_e32 v5, v44
	v_mov_b32_e32 v7, v45
	v_mov_b32_e32 v9, v46
	v_mov_b32_e32 v11, v47
	v_pk_add_f32 v[4:5], v[4:5], v[6:7]
	v_pk_add_f32 v[6:7], v[8:9], v[10:11]
	s_lshl_b32 s72, s12, 4
	v_pk_add_f32 v[4:5], v[4:5], v[6:7]
	v_mov_b64_e32 v[6:7], s[88:89]
	v_pk_add_f32 v[4:5], v[4:5], v[4:5] op_sel:[0,1] op_sel_hi:[1,0]
	s_nop 0
	v_bfe_u32 v5, v4, 16, 1
	v_add3_u32 v8, v4, v5, s41
	v_lshl_add_u64 v[4:5], v[24:25], 0, s[94:95]
	v_mad_u64_u32 v[6:7], s[10:11], v4, s40, v[6:7]
	v_mad_i32_i24 v7, v5, s40, v7
	s_lshl_b32 s10, s13, 7
	s_mov_b32 s11, s73
	v_lshl_add_u64 v[4:5], v[6:7], 0, s[10:11]
	s_lshl_b32 s10, s12, 5
	v_lshl_add_u64 v[4:5], v[4:5], 0, s[10:11]
	s_lshl_b32 s10, s16, 4
	s_or_b32 s10, s10, s13
	s_ashr_i32 s11, s10, 31
	v_lshl_add_u64 v[4:5], v[4:5], 0, v[22:23]
	s_lshl_b64 s[10:11], s[10:11], 14
	global_store_short_d16_hi v[4:5], v8, off
	v_lshl_add_u64 v[4:5], s[72:73], 0, v[16:17]
	s_add_u32 s10, s34, s10
	v_lshlrev_b64 v[4:5], 8, v[4:5]
	s_addc_u32 s11, s35, s11
	v_lshl_add_u64 v[4:5], s[10:11], 0, v[4:5]
	v_lshlrev_b32_e32 v22, 2, v20
	v_lshl_add_u64 v[4:5], v[4:5], 0, v[22:23]
	global_store_dwordx4 v[4:5], v[0:3], off
